# LayerNorm wave sums: the two 6-hop ds_bpermute butterflies per row replaced by permlane32/16 swaps and DPP row ops (same xor order, bit-identical sums)
# speedup vs baseline: 1.0032x; 1.0032x over previous
; DI float wave_sum(float v) {
; #pragma unroll
;     for (int o = 32; o >= 1; o >>= 1) v += __shfl_xor(v, o);
;     return v;
; }
; template <bool FINAL>
; DI void phase_ln(float* y, bf16_t* xb, float* stats, const float* g, const float* b, const int tid) {
;     ...
;     for (int row = blockIdx.x * 8 + wid; row < MTOK; row += gridDim.x * 8) {
;         float* yp = y + (size_t)row * 1024;
;         f32x4 v[4]; float s = 0.f;
; #pragma unroll
;         for (int k = 0; k < 4; ++k) { v[k] = __builtin_nontemporal_load((const f32x4*)(yp + k * 256 + lane * 4)); s += v[k][0] + v[k][1] + v[k][2] + v[k][3]; }
;         const float mean = wave_sum(s) * (1.0f / 1024.0f);
;         float q = 0.f;
; #pragma unroll
;         for (int k = 0; k < 4; ++k) { v[k] = v[k] - mean; q += v[k][0] * v[k][0] + v[k][1] * v[k][1] + v[k][2] * v[k][2] + v[k][3] * v[k][3]; }
;         const float var = wave_sum(q) * (1.0f / 1024.0f);
;         const float rs = 1.0f / sqrtf(var + 1e-5f);
;         if (!FINAL && lane == 0) { f32x2 sm = {mean, rs}; *(f32x2*)(stats + 2 * (size_t)row) = sm; }
.LBB0_90:
	v_ashrrev_i32_e32 v51, 31, v50
	v_lshlrev_b64 v[34:35], 12, v[50:51]
	v_lshl_add_u64 v[42:43], v[52:53], 0, v[34:35]
	global_load_dwordx4 v[38:41], v[42:43], off nt
	global_load_dwordx4 v[34:37], v[42:43], off offset:1024 nt
	global_load_dwordx4 v[46:49], v[42:43], off offset:2048 nt
	s_nop 0
	global_load_dwordx4 v[42:45], v[42:43], off offset:3072 nt
	s_mov_b32 s2, 0xf800000
	s_waitcnt vmcnt(2)
	v_mov_b32_e32 v62, v38
	v_mov_b32_e32 v63, v34
	v_mov_b32_e32 v64, v39
	v_mov_b32_e32 v65, v35
	v_pk_add_f32 v[62:63], v[62:63], v[64:65]
	v_mov_b32_e32 v64, v40
	v_mov_b32_e32 v65, v36
	v_pk_add_f32 v[62:63], v[64:65], v[62:63]
	v_mov_b32_e32 v64, v41
	v_mov_b32_e32 v65, v37
	v_pk_add_f32 v[62:63], v[64:65], v[62:63]
	s_nop 0
	v_add_f32_e32 v0, 0, v62
	v_add_f32_e32 v0, v0, v63
	s_waitcnt vmcnt(0)
	v_mov_b32_e32 v62, v46
	v_mov_b32_e32 v63, v42
	v_mov_b32_e32 v64, v47
	v_mov_b32_e32 v65, v43
	v_pk_add_f32 v[62:63], v[62:63], v[64:65]
	v_mov_b32_e32 v64, v48
	v_mov_b32_e32 v65, v44
	v_pk_add_f32 v[62:63], v[64:65], v[62:63]
	v_mov_b32_e32 v64, v49
	v_mov_b32_e32 v65, v45
	v_pk_add_f32 v[62:63], v[64:65], v[62:63]
	s_nop 0
	v_add_f32_e32 v0, v0, v62
	v_add_f32_e32 v0, v0, v63
	v_mov_b32_e32 v62, v0
	v_mov_b32_e32 v66, v0
	s_nop 1
	v_permlane32_swap_b32_e32 v62, v66
	v_add_f32_e32 v0, v62, v66
	v_mov_b32_e32 v62, v0
	v_mov_b32_e32 v66, v0
	s_nop 1
	v_permlane16_swap_b32_e32 v62, v66
	v_add_f32_e32 v0, v62, v66
	s_nop 1
	v_add_f32_dpp v62, v0, v0 row_ror:8 row_mask:0xf bank_mask:0xf
	s_nop 1
	v_add_f32_dpp v66, v62, v62 row_shl:4 row_mask:0xf bank_mask:0x5
	v_add_f32_dpp v66, v62, v62 row_shr:4 row_mask:0xf bank_mask:0xa
	s_nop 1
	v_add_f32_dpp v62, v66, v66 quad_perm:[2,3,0,1] row_mask:0xf bank_mask:0xf
	s_nop 1
	v_add_f32_dpp v66, v62, v62 quad_perm:[1,0,3,2] row_mask:0xf bank_mask:0xf
	v_mov_b32_e32 v62, v66
	v_fmamk_f32 v39, v62, 0xba800000, v39
	v_fmamk_f32 v35, v62, 0xba800000, v35
	v_fmac_f32_e32 v38, 0xba800000, v62
	v_mul_f32_e32 v0, v39, v39
	v_fmac_f32_e32 v34, 0xba800000, v62
	v_mul_f32_e32 v63, v35, v35
	v_fmamk_f32 v40, v62, 0xba800000, v40
	v_fmac_f32_e32 v0, v38, v38
	v_fmamk_f32 v36, v62, 0xba800000, v36
	v_fmac_f32_e32 v63, v34, v34
	v_fmamk_f32 v41, v62, 0xba800000, v41
	v_fmac_f32_e32 v0, v40, v40
	v_fmamk_f32 v37, v62, 0xba800000, v37
	v_fmac_f32_e32 v63, v36, v36
	v_fmac_f32_e32 v0, v41, v41
	v_fmac_f32_e32 v63, v37, v37
	v_fmamk_f32 v47, v62, 0xba800000, v47
	v_add_f32_e32 v0, v0, v63
	v_fmac_f32_e32 v46, 0xba800000, v62
	v_mul_f32_e32 v63, v47, v47
	v_fmamk_f32 v48, v62, 0xba800000, v48
	v_fmac_f32_e32 v63, v46, v46
	v_fmamk_f32 v49, v62, 0xba800000, v49
	v_fmac_f32_e32 v63, v48, v48
	v_fmac_f32_e32 v63, v49, v49
	v_fmamk_f32 v43, v62, 0xba800000, v43
	v_add_f32_e32 v0, v63, v0
	v_fmac_f32_e32 v42, 0xba800000, v62
	v_mul_f32_e32 v63, v43, v43
	v_fmamk_f32 v44, v62, 0xba800000, v44
	v_fmac_f32_e32 v63, v42, v42
	v_fmamk_f32 v45, v62, 0xba800000, v45
	v_fmac_f32_e32 v63, v44, v44
	v_fmac_f32_e32 v63, v45, v45
	v_add_f32_e32 v0, v63, v0
	v_mov_b32_e32 v63, v0
	v_mov_b32_e32 v66, v0
	s_nop 1
	v_permlane32_swap_b32_e32 v63, v66
	v_add_f32_e32 v0, v63, v66
	v_mov_b32_e32 v63, v0
	v_mov_b32_e32 v66, v0
	s_nop 1
	v_permlane16_swap_b32_e32 v63, v66
	v_add_f32_e32 v0, v63, v66
	s_nop 1
	v_add_f32_dpp v63, v0, v0 row_ror:8 row_mask:0xf bank_mask:0xf
	s_nop 1
	v_add_f32_dpp v66, v63, v63 row_shl:4 row_mask:0xf bank_mask:0x5
	v_add_f32_dpp v66, v63, v63 row_shr:4 row_mask:0xf bank_mask:0xa
	s_nop 1
	v_add_f32_dpp v63, v66, v66 quad_perm:[2,3,0,1] row_mask:0xf bank_mask:0xf
	s_nop 1
	v_add_f32_dpp v0, v63, v63 quad_perm:[1,0,3,2] row_mask:0xf bank_mask:0xf
	v_fmamk_f32 v0, v0, 0x3a800000, v235
	v_cmp_gt_f32_e32 vcc, s2, v0
	v_mul_f32_e32 v63, 0x4f800000, v0
	s_nop 0
	v_cndmask_b32_e32 v0, v0, v63, vcc
	v_sqrt_f32_e32 v63, v0
	s_nop 0
	v_add_u32_e32 v64, -1, v63
	v_fma_f32 v65, -v64, v63, v0
	v_cmp_ge_f32_e64 s[4:5], 0, v65
	v_add_u32_e32 v65, 1, v63
	s_nop 0
	v_cndmask_b32_e64 v64, v63, v64, s[4:5]
	v_fma_f32 v63, -v65, v63, v0
	v_cmp_lt_f32_e64 s[4:5], 0, v63
	s_nop 1
	v_cndmask_b32_e64 v63, v64, v65, s[4:5]
	v_mul_f32_e32 v64, 0x37800000, v63
	v_cndmask_b32_e32 v63, v63, v64, vcc
	v_cmp_class_f32_e32 vcc, v0, v236
	s_nop 1
	v_cndmask_b32_e32 v0, v63, v0, vcc
	v_div_scale_f32 v63, s[4:5], v0, v0, 1.0
	v_rcp_f32_e32 v64, v63
	s_nop 0
	v_fma_f32 v65, -v63, v64, 1.0
	v_fmac_f32_e32 v64, v65, v64
	v_div_scale_f32 v65, vcc, 1.0, v0, 1.0
	v_mul_f32_e32 v66, v65, v64
	v_fma_f32 v67, -v63, v66, v65
	v_fmac_f32_e32 v66, v67, v64
	v_fma_f32 v63, -v63, v66, v65
	v_div_fmas_f32 v63, v63, v64, v66
	v_div_fixup_f32 v0, v63, v0, 1.0
	s_and_saveexec_b64 s[4:5], s[0:1]
	s_cbranch_execz .LBB0_89
	v_readlane_b32 s42, v251, 1
	v_readlane_b32 s43, v251, 2
	v_mul_f32_e32 v62, 0x3a800000, v62
	v_mov_b32_e32 v63, v0
	v_lshl_add_u64 v[64:65], v[50:51], 3, s[42:43]
	global_store_dwordx2 v[64:65], v[62:63], off
	s_branch .LBB0_89

; DI unsigned pk2(float lo, float hi) { f32x2 v = {lo, hi}; bf2_t b = __builtin_convertvector(v, bf2_t); return __builtin_bit_cast(unsigned, b); }
; template <bool FINAL>
; DI void phase_ln(float* y, bf16_t* xb, float* stats, const float* g, const float* b, const int tid) {
;     ...
;     for (int row = blockIdx.x * 8 + wid; row < MTOK; row += gridDim.x * 8) {
;         float* yp = y + (size_t)row * 1024;
;         f32x4 v[4]; float s = 0.f;
; #pragma unroll
;         for (int k = 0; k < 4; ++k) { v[k] = __builtin_nontemporal_load((const f32x4*)(yp + k * 256 + lane * 4)); s += v[k][0] + v[k][1] + v[k][2] + v[k][3]; }
;         const float mean = wave_sum(s) * (1.0f / 1024.0f);
;         float q = 0.f;
; #pragma unroll
;         for (int k = 0; k < 4; ++k) { v[k] = v[k] - mean; q += v[k][0] * v[k][0] + v[k][1] * v[k][1] + v[k][2] * v[k][2] + v[k][3] * v[k][3]; }
;         const float var = wave_sum(q) * (1.0f / 1024.0f);
;         const float rs = 1.0f / sqrtf(var + 1e-5f);
;         if (!FINAL && lane == 0) { f32x2 sm = {mean, rs}; *(f32x2*)(stats + 2 * (size_t)row) = sm; }
; #pragma unroll
;         for (int k = 0; k < 4; ++k) { const f32x4 o = v[k] * rs * gv[k] + bv[k];
;             if (FINAL) *(f32x4*)(yp + k * 256 + lane * 4) = o;
;             else { u32x2 w; w.x = pk2(o[0], o[1]); w.y = pk2(o[2], o[3]); *(u32x2*)(xb + (size_t)row * 1024 + k * 256 + lane * 4) = w; } }
;     }
.LBB0_538:
	v_ashrrev_i32_e32 v55, 31, v54
	v_lshlrev_b64 v[34:35], 12, v[54:55]
	v_lshl_add_u64 v[56:57], v[52:53], 0, v[34:35]
	global_load_dwordx4 v[38:41], v[56:57], off nt
	global_load_dwordx4 v[34:37], v[56:57], off offset:1024 nt
	global_load_dwordx4 v[46:49], v[56:57], off offset:2048 nt
	global_load_dwordx4 v[42:45], v[56:57], off offset:3072 nt
	v_add_u32_e32 v54, s9, v54
	s_waitcnt vmcnt(2)
	v_mov_b32_e32 v64, v38
	v_mov_b32_e32 v65, v34
	v_mov_b32_e32 v66, v39
	v_mov_b32_e32 v67, v35
	v_pk_add_f32 v[64:65], v[64:65], v[66:67]
	v_mov_b32_e32 v66, v40
	v_mov_b32_e32 v67, v36
	v_pk_add_f32 v[64:65], v[66:67], v[64:65]
	v_mov_b32_e32 v66, v41
	v_mov_b32_e32 v67, v37
	v_pk_add_f32 v[64:65], v[66:67], v[64:65]
	s_nop 0
	v_add_f32_e32 v0, 0, v64
	v_add_f32_e32 v0, v0, v65
	s_waitcnt vmcnt(0)
	v_mov_b32_e32 v64, v46
	v_mov_b32_e32 v65, v42
	v_mov_b32_e32 v66, v47
	v_mov_b32_e32 v67, v43
	v_pk_add_f32 v[64:65], v[64:65], v[66:67]
	v_mov_b32_e32 v66, v48
	v_mov_b32_e32 v67, v44
	v_pk_add_f32 v[64:65], v[66:67], v[64:65]
	v_mov_b32_e32 v66, v49
	v_mov_b32_e32 v67, v45
	v_pk_add_f32 v[64:65], v[66:67], v[64:65]
	s_nop 0
	v_add_f32_e32 v0, v0, v64
	v_add_f32_e32 v0, v0, v65
	v_mov_b32_e32 v55, v0
	v_mov_b32_e32 v66, v0
	s_nop 1
	v_permlane32_swap_b32_e32 v55, v66
	v_add_f32_e32 v0, v55, v66
	v_mov_b32_e32 v55, v0
	v_mov_b32_e32 v66, v0
	s_nop 1
	v_permlane16_swap_b32_e32 v55, v66
	v_add_f32_e32 v0, v55, v66
	s_nop 1
	v_add_f32_dpp v55, v0, v0 row_ror:8 row_mask:0xf bank_mask:0xf
	s_nop 1
	v_add_f32_dpp v66, v55, v55 row_shl:4 row_mask:0xf bank_mask:0x5
	v_add_f32_dpp v66, v55, v55 row_shr:4 row_mask:0xf bank_mask:0xa
	s_nop 1
	v_add_f32_dpp v55, v66, v66 quad_perm:[2,3,0,1] row_mask:0xf bank_mask:0xf
	s_nop 1
	v_add_f32_dpp v0, v55, v55 quad_perm:[1,0,3,2] row_mask:0xf bank_mask:0xf
	v_fmac_f32_e32 v39, 0xba800000, v0
	v_fmac_f32_e32 v35, 0xba800000, v0
	v_fmamk_f32 v38, v0, 0xba800000, v38
	v_mul_f32_e32 v55, v39, v39
	v_fmamk_f32 v64, v0, 0xba800000, v36
	v_fmamk_f32 v34, v0, 0xba800000, v34
	v_mul_f32_e32 v36, v35, v35
	v_fmamk_f32 v40, v0, 0xba800000, v40
	v_fmac_f32_e32 v55, v38, v38
	v_fmac_f32_e32 v36, v34, v34
	v_fmamk_f32 v41, v0, 0xba800000, v41
	v_fmac_f32_e32 v55, v40, v40
	v_fmamk_f32 v65, v0, 0xba800000, v37
	v_fmac_f32_e32 v36, v64, v64
	v_fmamk_f32 v47, v0, 0xba800000, v47
	v_fmamk_f32 v43, v0, 0xba800000, v43
	v_fmac_f32_e32 v55, v41, v41
	v_fmac_f32_e32 v36, v65, v65
	v_fmac_f32_e32 v46, 0xba800000, v0
	v_fmac_f32_e32 v42, 0xba800000, v0
	v_mov_b32_e32 v66, v43
	v_mov_b32_e32 v67, v47
	v_add_f32_e32 v55, v55, v36
	v_fmamk_f32 v48, v0, 0xba800000, v48
	v_fmamk_f32 v44, v0, 0xba800000, v44
	v_mov_b32_e32 v36, v42
	v_mov_b32_e32 v37, v46
	v_pk_mul_f32 v[66:67], v[66:67], v[66:67]
	v_fmamk_f32 v49, v0, 0xba800000, v49
	v_fmamk_f32 v45, v0, 0xba800000, v45
	v_pk_fma_f32 v[36:37], v[36:37], v[36:37], v[66:67]
	v_mov_b32_e32 v66, v44
	v_mov_b32_e32 v67, v48
	v_pk_fma_f32 v[36:37], v[66:67], v[66:67], v[36:37]
	v_mov_b32_e32 v66, v45
	v_mov_b32_e32 v67, v49
	v_pk_fma_f32 v[36:37], v[66:67], v[66:67], v[36:37]
	s_nop 0
	v_add_f32_e32 v0, v37, v55
	v_add_f32_e32 v0, v36, v0
	v_mov_b32_e32 v36, v0
	v_mov_b32_e32 v66, v0
	s_nop 1
	v_permlane32_swap_b32_e32 v36, v66
	v_add_f32_e32 v0, v36, v66
	v_mov_b32_e32 v36, v0
	v_mov_b32_e32 v66, v0
	s_nop 1
	v_permlane16_swap_b32_e32 v36, v66
	v_add_f32_e32 v0, v36, v66
	s_nop 1
	v_add_f32_dpp v36, v0, v0 row_ror:8 row_mask:0xf bank_mask:0xf
	s_nop 1
	v_add_f32_dpp v66, v36, v36 row_shl:4 row_mask:0xf bank_mask:0x5
	v_add_f32_dpp v66, v36, v36 row_shr:4 row_mask:0xf bank_mask:0xa
	s_nop 1
	v_add_f32_dpp v36, v66, v66 quad_perm:[2,3,0,1] row_mask:0xf bank_mask:0xf
	s_nop 1
	v_add_f32_dpp v0, v36, v36 quad_perm:[1,0,3,2] row_mask:0xf bank_mask:0xf
	v_fmamk_f32 v0, v0, 0x3a800000, v235
	v_cmp_gt_f32_e32 vcc, s2, v0
	v_mul_f32_e32 v36, 0x4f800000, v0
	s_nop 0
	v_cndmask_b32_e32 v0, v0, v36, vcc
	v_sqrt_f32_e32 v36, v0
	s_nop 0
	v_add_u32_e32 v37, -1, v36
	v_fma_f32 v55, -v37, v36, v0
	v_cmp_ge_f32_e64 s[0:1], 0, v55
	v_add_u32_e32 v55, 1, v36
	s_nop 0
	v_cndmask_b32_e64 v37, v36, v37, s[0:1]
	v_fma_f32 v36, -v55, v36, v0
	v_cmp_lt_f32_e64 s[0:1], 0, v36
	s_nop 1
	v_cndmask_b32_e64 v36, v37, v55, s[0:1]
	v_mul_f32_e32 v37, 0x37800000, v36
	v_cndmask_b32_e32 v36, v36, v37, vcc
	v_cmp_class_f32_e32 vcc, v0, v236
	s_nop 1
	v_cndmask_b32_e32 v0, v36, v0, vcc
	v_div_scale_f32 v36, s[0:1], v0, v0, 1.0
	v_rcp_f32_e32 v37, v36
	s_nop 0
	v_fma_f32 v55, -v36, v37, 1.0
	v_fmac_f32_e32 v37, v55, v37
	v_div_scale_f32 v55, vcc, 1.0, v0, 1.0
	v_mul_f32_e32 v63, v55, v37
	v_fma_f32 v66, -v36, v63, v55
	v_fmac_f32_e32 v63, v66, v37
	v_fma_f32 v36, -v36, v63, v55
	v_div_fmas_f32 v36, v36, v37, v63
	v_div_fixup_f32 v0, v36, v0, 1.0
	v_pk_mul_f32 v[36:37], v[38:39], v[0:1] op_sel_hi:[1,0]
	v_pk_mul_f32 v[38:39], v[40:41], v[0:1] op_sel_hi:[1,0]
	v_pk_fma_f32 v[36:37], v[2:3], v[36:37], v[10:11]
	v_pk_fma_f32 v[38:39], v[4:5], v[38:39], v[12:13]
	global_store_dwordx4 v[56:57], v[36:39], off
	v_pk_mul_f32 v[34:35], v[34:35], v[0:1] op_sel_hi:[1,0]
	v_cmp_lt_i32_e32 vcc, s8, v54
	v_pk_mul_f32 v[36:37], v[64:65], v[0:1] op_sel_hi:[1,0]
	v_pk_fma_f32 v[34:35], v[6:7], v[34:35], v[14:15]
	v_pk_fma_f32 v[36:37], v[8:9], v[36:37], v[16:17]
	global_store_dwordx4 v[56:57], v[34:37], off offset:1024
	s_or_b64 s[6:7], vcc, s[6:7]
	s_nop 0
	v_pk_mul_f32 v[34:35], v[46:47], v[0:1] op_sel_hi:[1,0]
	v_pk_mul_f32 v[36:37], v[48:49], v[0:1] op_sel_hi:[1,0]
	v_pk_fma_f32 v[34:35], v[18:19], v[34:35], v[26:27]
	v_pk_fma_f32 v[36:37], v[20:21], v[36:37], v[28:29]
	global_store_dwordx4 v[56:57], v[34:37], off offset:2048
	s_nop 1
	v_pk_mul_f32 v[34:35], v[42:43], v[0:1] op_sel_hi:[1,0]
	v_pk_mul_f32 v[36:37], v[44:45], v[0:1] op_sel_hi:[1,0]
	v_pk_fma_f32 v[34:35], v[22:23], v[34:35], v[30:31]
	v_pk_fma_f32 v[36:37], v[24:25], v[36:37], v[32:33]
	global_store_dwordx4 v[56:57], v[34:37], off offset:3072
	s_andn2_b64 exec, exec, s[6:7]
	s_cbranch_execnz .LBB0_538

; template <bool FINAL>
; DI void phase_ln(float* y, bf16_t* xb, float* stats, const float* g, const float* b, const int tid) {
;     ...
;     for (int row = blockIdx.x * 8 + wid; row < MTOK; row += gridDim.x * 8) {
;         float* yp = y + (size_t)row * 1024;
;         f32x4 v[4]; float s = 0.f;
; #pragma unroll
;         for (int k = 0; k < 4; ++k) { v[k] = __builtin_nontemporal_load((const f32x4*)(yp + k * 256 + lane * 4)); s += v[k][0] + v[k][1] + v[k][2] + v[k][3]; }
;         const float mean = wave_sum(s) * (1.0f / 1024.0f);
;         float q = 0.f;
; #pragma unroll
;         for (int k = 0; k < 4; ++k) { v[k] = v[k] - mean; q += v[k][0] * v[k][0] + v[k][1] * v[k][1] + v[k][2] * v[k][2] + v[k][3] * v[k][3]; }
;         const float var = wave_sum(q) * (1.0f / 1024.0f);
;         const float rs = 1.0f / sqrtf(var + 1e-5f);
;         if (!FINAL && lane == 0) { f32x2 sm = {mean, rs}; *(f32x2*)(stats + 2 * (size_t)row) = sm; }
.LBB0_544:
	v_ashrrev_i32_e32 v51, 31, v50
	v_lshlrev_b64 v[34:35], 12, v[50:51]
	v_lshl_add_u64 v[42:43], v[52:53], 0, v[34:35]
	global_load_dwordx4 v[38:41], v[42:43], off nt
	global_load_dwordx4 v[34:37], v[42:43], off offset:1024 nt
	global_load_dwordx4 v[46:49], v[42:43], off offset:2048 nt
	s_nop 0
	global_load_dwordx4 v[42:45], v[42:43], off offset:3072 nt
	s_mov_b32 s2, 0xf800000
	s_waitcnt vmcnt(2)
	v_mov_b32_e32 v62, v38
	v_mov_b32_e32 v63, v34
	v_mov_b32_e32 v64, v39
	v_mov_b32_e32 v65, v35
	v_pk_add_f32 v[62:63], v[62:63], v[64:65]
	v_mov_b32_e32 v64, v40
	v_mov_b32_e32 v65, v36
	v_pk_add_f32 v[62:63], v[64:65], v[62:63]
	v_mov_b32_e32 v64, v41
	v_mov_b32_e32 v65, v37
	v_pk_add_f32 v[62:63], v[64:65], v[62:63]
	s_nop 0
	v_add_f32_e32 v0, 0, v62
	v_add_f32_e32 v0, v0, v63
	s_waitcnt vmcnt(0)
	v_mov_b32_e32 v62, v46
	v_mov_b32_e32 v63, v42
	v_mov_b32_e32 v64, v47
	v_mov_b32_e32 v65, v43
	v_pk_add_f32 v[62:63], v[62:63], v[64:65]
	v_mov_b32_e32 v64, v48
	v_mov_b32_e32 v65, v44
	v_pk_add_f32 v[62:63], v[64:65], v[62:63]
	v_mov_b32_e32 v64, v49
	v_mov_b32_e32 v65, v45
	v_pk_add_f32 v[62:63], v[64:65], v[62:63]
	s_nop 0
	v_add_f32_e32 v0, v0, v62
	v_add_f32_e32 v0, v0, v63
	v_mov_b32_e32 v62, v0
	v_mov_b32_e32 v66, v0
	s_nop 1
	v_permlane32_swap_b32_e32 v62, v66
	v_add_f32_e32 v0, v62, v66
	v_mov_b32_e32 v62, v0
	v_mov_b32_e32 v66, v0
	s_nop 1
	v_permlane16_swap_b32_e32 v62, v66
	v_add_f32_e32 v0, v62, v66
	s_nop 1
	v_add_f32_dpp v62, v0, v0 row_ror:8 row_mask:0xf bank_mask:0xf
	s_nop 1
	v_add_f32_dpp v66, v62, v62 row_shl:4 row_mask:0xf bank_mask:0x5
	v_add_f32_dpp v66, v62, v62 row_shr:4 row_mask:0xf bank_mask:0xa
	s_nop 1
	v_add_f32_dpp v62, v66, v66 quad_perm:[2,3,0,1] row_mask:0xf bank_mask:0xf
	s_nop 1
	v_add_f32_dpp v66, v62, v62 quad_perm:[1,0,3,2] row_mask:0xf bank_mask:0xf
	v_mov_b32_e32 v62, v66
	v_fmamk_f32 v39, v62, 0xba800000, v39
	v_fmamk_f32 v35, v62, 0xba800000, v35
	v_fmac_f32_e32 v38, 0xba800000, v62
	v_mul_f32_e32 v0, v39, v39
	v_fmac_f32_e32 v34, 0xba800000, v62
	v_mul_f32_e32 v63, v35, v35
	v_fmamk_f32 v40, v62, 0xba800000, v40
	v_fmac_f32_e32 v0, v38, v38
	v_fmamk_f32 v36, v62, 0xba800000, v36
	v_fmac_f32_e32 v63, v34, v34
	v_fmamk_f32 v41, v62, 0xba800000, v41
	v_fmac_f32_e32 v0, v40, v40
	v_fmamk_f32 v37, v62, 0xba800000, v37
	v_fmac_f32_e32 v63, v36, v36
	v_fmac_f32_e32 v0, v41, v41
	v_fmac_f32_e32 v63, v37, v37
	v_fmamk_f32 v47, v62, 0xba800000, v47
	v_add_f32_e32 v0, v0, v63
	v_fmac_f32_e32 v46, 0xba800000, v62
	v_mul_f32_e32 v63, v47, v47
	v_fmamk_f32 v48, v62, 0xba800000, v48
	v_fmac_f32_e32 v63, v46, v46
	v_fmamk_f32 v49, v62, 0xba800000, v49
	v_fmac_f32_e32 v63, v48, v48
	v_fmac_f32_e32 v63, v49, v49
	v_fmamk_f32 v43, v62, 0xba800000, v43
	v_add_f32_e32 v0, v63, v0
	v_fmac_f32_e32 v42, 0xba800000, v62
	v_mul_f32_e32 v63, v43, v43
	v_fmamk_f32 v44, v62, 0xba800000, v44
	v_fmac_f32_e32 v63, v42, v42
	v_fmamk_f32 v45, v62, 0xba800000, v45
	v_fmac_f32_e32 v63, v44, v44
	v_fmac_f32_e32 v63, v45, v45
	v_add_f32_e32 v0, v63, v0
	v_mov_b32_e32 v63, v0
	v_mov_b32_e32 v66, v0
	s_nop 1
	v_permlane32_swap_b32_e32 v63, v66
	v_add_f32_e32 v0, v63, v66
	v_mov_b32_e32 v63, v0
	v_mov_b32_e32 v66, v0
	s_nop 1
	v_permlane16_swap_b32_e32 v63, v66
	v_add_f32_e32 v0, v63, v66
	s_nop 1
	v_add_f32_dpp v63, v0, v0 row_ror:8 row_mask:0xf bank_mask:0xf
	s_nop 1
	v_add_f32_dpp v66, v63, v63 row_shl:4 row_mask:0xf bank_mask:0x5
	v_add_f32_dpp v66, v63, v63 row_shr:4 row_mask:0xf bank_mask:0xa
	s_nop 1
	v_add_f32_dpp v63, v66, v66 quad_perm:[2,3,0,1] row_mask:0xf bank_mask:0xf
	s_nop 1
	v_add_f32_dpp v0, v63, v63 quad_perm:[1,0,3,2] row_mask:0xf bank_mask:0xf
	v_fmamk_f32 v0, v0, 0x3a800000, v235
	v_cmp_gt_f32_e32 vcc, s2, v0
	v_mul_f32_e32 v63, 0x4f800000, v0
	s_nop 0
	v_cndmask_b32_e32 v0, v0, v63, vcc
	v_sqrt_f32_e32 v63, v0
	s_nop 0
	v_add_u32_e32 v64, -1, v63
	v_fma_f32 v65, -v64, v63, v0
	v_cmp_ge_f32_e64 s[4:5], 0, v65
	v_add_u32_e32 v65, 1, v63
	s_nop 0
	v_cndmask_b32_e64 v64, v63, v64, s[4:5]
	v_fma_f32 v63, -v65, v63, v0
	v_cmp_lt_f32_e64 s[4:5], 0, v63
	s_nop 1
	v_cndmask_b32_e64 v63, v64, v65, s[4:5]
	v_mul_f32_e32 v64, 0x37800000, v63
	v_cndmask_b32_e32 v63, v63, v64, vcc
	v_cmp_class_f32_e32 vcc, v0, v236
	s_nop 1
	v_cndmask_b32_e32 v0, v63, v0, vcc
	v_div_scale_f32 v63, s[4:5], v0, v0, 1.0
	v_rcp_f32_e32 v64, v63
	s_nop 0
	v_fma_f32 v65, -v63, v64, 1.0
	v_fmac_f32_e32 v64, v65, v64
	v_div_scale_f32 v65, vcc, 1.0, v0, 1.0
	v_mul_f32_e32 v66, v65, v64
	v_fma_f32 v67, -v63, v66, v65
	v_fmac_f32_e32 v66, v67, v64
	v_fma_f32 v63, -v63, v66, v65
	v_div_fmas_f32 v63, v63, v64, v66
	v_div_fixup_f32 v0, v63, v0, 1.0
	s_and_saveexec_b64 s[4:5], s[0:1]
	s_cbranch_execz .LBB0_543
	v_readlane_b32 s38, v251, 1
	v_readlane_b32 s39, v251, 2
	v_mul_f32_e32 v62, 0x3a800000, v62
	v_mov_b32_e32 v63, v0
	v_lshl_add_u64 v[64:65], v[50:51], 3, s[38:39]
	global_store_dwordx2 v[64:65], v[62:63], off
	s_branch .LBB0_543
